# scan: static s_setprio 2 for the four heavy waves (q tiles 4-7) from the first intra-chunk step on
# baseline (speedup 1.0000x reference)
.LBB0_628:
	s_bitcmp1_b32 s57, 0
	s_cselect_b32 s50, 0x900, 0
	s_add_i32 s61, s50, 0
	s_add_i32 s61, s61, 0x1c800
	s_waitcnt vmcnt(8)
	ds_write_b128 v184, v[4:7]
	s_waitcnt vmcnt(7)
	ds_write_b128 v185, v[8:11]
	s_waitcnt vmcnt(6)
	ds_write_b128 v186, v[12:15]
	s_waitcnt vmcnt(5)
	ds_write_b128 v187, v[16:19]
	s_waitcnt vmcnt(4)
	ds_write_b128 v188, v[20:23]
	s_waitcnt vmcnt(3)
	ds_write_b128 v189, v[24:27]
	s_waitcnt vmcnt(2)
	ds_write_b128 v190, v[28:31]
	s_waitcnt vmcnt(1)
	ds_write_b128 v191, v[32:35]
	v_lshl_add_u32 v1, v160, 2, s61
	ds_read_b32 v2, v1 offset:1536
	s_waitcnt vmcnt(0)
	v_lshlrev_b32_e32 v96, 16, v36
	v_and_b32_e32 v97, 0xffff0000, v36
	ds_write_b16 v165, v36
	ds_write_b16_d16_hi v165, v36 offset:272
	ds_write_b16 v165, v37 offset:544
	ds_write_b16_d16_hi v165, v37 offset:816
	ds_write_b16 v165, v38 offset:1088
	ds_write_b16_d16_hi v165, v38 offset:1360
	ds_write_b16 v165, v39 offset:1632
	ds_write_b16_d16_hi v165, v39 offset:1904
	s_waitcnt lgkmcnt(8)
	v_pk_mul_f32 v[96:97], v[2:3], v[96:97] op_sel_hi:[0,1]
	v_cvt_pk_bf16_f32 v1, v96, v97
	v_lshlrev_b32_e32 v96, 16, v37
	v_and_b32_e32 v97, 0xffff0000, v37
	v_pk_mul_f32 v[96:97], v[2:3], v[96:97] op_sel_hi:[0,1]
	v_cvt_pk_bf16_f32 v3, v96, v97
	v_lshlrev_b32_e32 v96, 16, v38
	v_and_b32_e32 v97, 0xffff0000, v38
	v_pk_mul_f32 v[96:97], v[2:3], v[96:97] op_sel_hi:[0,1]
	v_cvt_pk_bf16_f32 v98, v96, v97
	v_lshlrev_b32_e32 v96, 16, v39
	v_and_b32_e32 v97, 0xffff0000, v39
	v_pk_mul_f32 v[96:97], v[2:3], v[96:97] op_sel_hi:[0,1]
	v_cvt_pk_bf16_f32 v96, v96, v97
	ds_write_b16 v166, v1
	ds_write_b16_d16_hi v166, v1 offset:272
	ds_write_b16 v166, v3 offset:544
	ds_write_b16_d16_hi v166, v3 offset:816
	ds_write_b16 v166, v98 offset:1088
	ds_write_b16_d16_hi v166, v98 offset:1360
	ds_write_b16 v166, v96 offset:1632
	ds_write_b16_d16_hi v166, v96 offset:1904
	s_and_saveexec_b64 s[50:51], s[14:15]
	v_cvt_pk_bf16_f32 v1, v2, s0
	ds_write_b16 v167, v1
	s_or_b64 exec, exec, s[50:51]
	s_cmp_lt_u32 s57, 2
	s_waitcnt lgkmcnt(0)
	s_barrier
	s_cbranch_scc1 .LBB0_655
	v_readfirstlane_b32 s98, v170
	s_cmp_ge_u32 s98, 64
	s_cbranch_scc0 .Lscan_noprio
	s_setprio 2
.Lscan_noprio:
	v_mov_b32_e32 v96, 0
	v_mov_b32_e32 v100, 0
	v_mov_b32_e32 v101, 0
	v_mov_b32_e32 v102, 0
	v_mov_b32_e32 v103, 0
	s_and_saveexec_b64 s[50:51], s[16:17]
	s_cbranch_execz .LBB0_633
	ds_read_b128 v[98:101], v169
	ds_read_b128 v[102:105], v169 offset:64
	ds_read_b128 v[214:217], v169 offset:128
	ds_read_b128 v[218:221], v169 offset:192
	ds_read_b128 v[236:239], v169 offset:256
	ds_read_b128 v[240:243], v169 offset:320
	ds_read_b128 v[244:247], v169 offset:384
	ds_read_b128 v[248:251], v169 offset:448
	s_waitcnt lgkmcnt(7)
	v_mfma_f32_16x16x32_bf16 v[98:101], v[98:101], v[40:43], 0
	s_waitcnt lgkmcnt(6)
	v_mfma_f32_16x16x32_bf16 v[98:101], v[102:105], v[44:47], v[98:101]
	s_waitcnt lgkmcnt(5)
	v_mfma_f32_16x16x32_bf16 v[98:101], v[214:217], v[48:51], v[98:101]
	s_waitcnt lgkmcnt(4)
	v_mfma_f32_16x16x32_bf16 v[98:101], v[218:221], v[52:55], v[98:101]
	s_waitcnt lgkmcnt(3)
	v_mfma_f32_16x16x32_bf16 v[98:101], v[236:239], v[56:59], v[98:101]
	s_waitcnt lgkmcnt(2)
	v_mfma_f32_16x16x32_bf16 v[98:101], v[240:243], v[60:63], v[98:101]
	s_waitcnt lgkmcnt(1)
	v_mfma_f32_16x16x32_bf16 v[98:101], v[244:247], v[64:67], v[98:101]
	s_waitcnt lgkmcnt(0)
	v_mfma_f32_16x16x32_bf16 v[100:103], v[248:251], v[68:71], v[98:101]

.LBB0_655:
	s_setprio 0
	s_cmp_eq_u32 s57, 33
	s_cselect_b64 s[50:51], -1, 0
	s_and_b64 vcc, exec, s[50:51]
	s_cbranch_vccnz .LBB0_678
